# v84 + the peeled iteration's 16 fragment ds_reads issued at the top of the unit header (scalar header work overlaps their latency)
# speedup vs baseline: 1.0119x; 1.0010x over previous
.LBB0_136:
	ds_read_b128 v[96:99], v183
	ds_read_b128 v[100:103], v183 offset:1024
	ds_read_b128 v[112:115], v183 offset:2048
	ds_read_b128 v[120:123], v183 offset:3072
	ds_read_b128 v[144:147], v184
	ds_read_b128 v[170:173], v184 offset:1024
	ds_read_b128 v[186:189], v184 offset:2048
	ds_read_b128 v[190:193], v184 offset:3072
	ds_read_b128 v[198:201], v185
	ds_read_b128 v[206:209], v185 offset:1024
	ds_read_b128 v[210:213], v185 offset:2048
	ds_read_b128 v[214:217], v185 offset:3072
	ds_read_b128 v[218:221], v185 offset:4096
	ds_read_b128 v[222:225], v185 offset:5120
	ds_read_b128 v[226:229], v185 offset:6144
	ds_read_b128 v[230:233], v185 offset:7168
	s_add_i32 s96, s96, 1
	s_mul_i32 s12, s96, s99
	s_mul_hi_u32 s13, s96, s88
	s_add_i32 s13, s13, s12
	s_mul_i32 s12, s96, s88
	s_add_u32 s78, s12, s2
	s_addc_u32 s79, s13, s3
	v_cmp_gt_i64_e32 vcc, s[78:79], v[168:169]
	v_cmp_lt_i64_e64 s[12:13], s[78:79], v[166:167]
	s_cbranch_vccnz .LBB0_142
	s_ashr_i32 s14, s78, 31
	s_lshr_b32 s14, s14, 29
	s_add_i32 s14, s78, s14
	s_and_b32 s15, s14, -8
	s_sub_i32 s15, s78, s15
	s_cmp_gt_i32 s15, -1
	s_mov_b64 s[74:75], -1
	s_cbranch_scc0 .LBB0_139
	s_lshl_b32 s76, s15, 7
	s_mov_b64 s[74:75], 0

.LBB0_142:
	s_ashr_i32 s77, s76, 31
	s_lshl_b64 s[14:15], s[76:77], 19
	s_add_u32 s78, s48, s14
	s_addc_u32 s79, s49, s15
	s_and_b64 s[14:15], s[12:13], exec
	s_cselect_b32 s77, s79, s1
	s_cselect_b32 vcc_lo, s78, s0
	s_ashr_i32 s75, s74, 31
	s_lshl_b64 s[14:15], s[74:75], 19
	s_add_u32 s80, s16, s14
	s_addc_u32 s81, s17, s15
	s_and_b64 s[14:15], s[12:13], exec
	s_cselect_b32 s75, s81, s85
	s_cselect_b32 vcc_hi, s80, s84
	s_add_u32 s0, s0, 0x40080
	s_addc_u32 s1, s1, 0
	s_add_u32 s14, s84, 0x100
	s_addc_u32 s15, s85, 0
	s_mov_b32 s89, -2
	s_add_u32 s44, s0, 0xfffc0080
	s_addc_u32 s45, s1, -1
	s_cmp_eq_u32 s89, 12
	s_cselect_b32 s87, s77, s45
	s_cselect_b32 s86, vcc_lo, s44
	s_cselect_b32 s85, s75, s15
	s_cselect_b32 s84, vcc_hi, s14
	v_lshl_add_u64 v[194:195], s[0:1], 0, v[162:163]
	s_add_i32 m0, s92, 0xc000
	global_load_lds_dwordx4 v[194:195], off
	v_lshl_add_u64 v[194:195], s[0:1], 0, v[164:165]
	s_add_i32 m0, s92, 0xe000
	s_nop 0
	global_load_lds_dwordx4 v[194:195], off
	s_waitcnt vmcnt(8)
	s_waitcnt lgkmcnt(0)
	s_barrier
	s_setprio 1
	s_waitcnt lgkmcnt(0)
	v_mfma_f32_16x16x32_bf16 v[140:143], v[96:99], v[198:201], 0
	v_mfma_f32_16x16x32_bf16 v[136:139], v[112:115], v[198:201], 0
	v_mfma_f32_16x16x32_bf16 v[124:127], v[96:99], v[210:213], 0
	v_mfma_f32_16x16x32_bf16 v[116:119], v[112:115], v[210:213], 0
	v_mfma_f32_16x16x32_bf16 v[92:95], v[96:99], v[218:221], 0
	v_mfma_f32_16x16x32_bf16 v[88:91], v[112:115], v[218:221], 0
	v_mfma_f32_16x16x32_bf16 v[76:79], v[96:99], v[226:229], 0
	v_mfma_f32_16x16x32_bf16 v[72:75], v[112:115], v[226:229], 0
	v_mfma_f32_16x16x32_bf16 v[140:143], v[100:103], v[206:209], v[140:143]
	v_mfma_f32_16x16x32_bf16 v[136:139], v[120:123], v[206:209], v[136:139]
	v_mfma_f32_16x16x32_bf16 v[124:127], v[100:103], v[214:217], v[124:127]
	v_mfma_f32_16x16x32_bf16 v[116:119], v[120:123], v[214:217], v[116:119]
	v_mfma_f32_16x16x32_bf16 v[92:95], v[100:103], v[222:225], v[92:95]
	v_mfma_f32_16x16x32_bf16 v[88:91], v[120:123], v[222:225], v[88:91]
	v_mfma_f32_16x16x32_bf16 v[76:79], v[100:103], v[230:233], v[76:79]
	v_mfma_f32_16x16x32_bf16 v[72:75], v[120:123], v[230:233], v[72:75]
	s_setprio 0
	s_setprio 1
	v_mfma_f32_16x16x32_bf16 v[128:131], v[144:147], v[198:201], 0
	v_mfma_f32_16x16x32_bf16 v[132:135], v[186:189], v[198:201], 0
	v_mfma_f32_16x16x32_bf16 v[104:107], v[144:147], v[210:213], 0
	v_mfma_f32_16x16x32_bf16 v[108:111], v[186:189], v[210:213], 0
	v_mfma_f32_16x16x32_bf16 v[80:83], v[144:147], v[218:221], 0
	v_mfma_f32_16x16x32_bf16 v[84:87], v[186:189], v[218:221], 0
	v_mfma_f32_16x16x32_bf16 v[64:67], v[144:147], v[226:229], 0
	v_mfma_f32_16x16x32_bf16 v[68:71], v[186:189], v[226:229], 0
	v_mfma_f32_16x16x32_bf16 v[128:131], v[170:173], v[206:209], v[128:131]
	v_mfma_f32_16x16x32_bf16 v[132:135], v[190:193], v[206:209], v[132:135]
	v_mfma_f32_16x16x32_bf16 v[104:107], v[170:173], v[214:217], v[104:107]
	v_mfma_f32_16x16x32_bf16 v[108:111], v[190:193], v[214:217], v[108:111]
	v_mfma_f32_16x16x32_bf16 v[80:83], v[170:173], v[222:225], v[80:83]
	v_mfma_f32_16x16x32_bf16 v[84:87], v[190:193], v[222:225], v[84:87]
	v_mfma_f32_16x16x32_bf16 v[64:67], v[170:173], v[230:233], v[64:67]
	v_mfma_f32_16x16x32_bf16 v[68:71], v[190:193], v[230:233], v[68:71]
	s_setprio 0
	s_barrier
	s_add_i32 s44, s56, s91
	v_lshl_add_u64 v[194:195], s[84:85], 0, v[150:151]
	s_mov_b32 m0, s44
	ds_read_b128 v[198:201], v185 offset:16384
	ds_read_b128 v[206:209], v185 offset:17408
	ds_read_b128 v[210:213], v185 offset:18432
	ds_read_b128 v[214:217], v185 offset:19456
	ds_read_b128 v[218:221], v185 offset:20480
	ds_read_b128 v[222:225], v185 offset:21504
	ds_read_b128 v[226:229], v185 offset:22528
	ds_read_b128 v[230:233], v185 offset:23552
	global_load_lds_dwordx4 v[194:195], off
	s_add_i32 m0, s44, 0x2000
	s_add_u32 s44, s84, 0x40000
	v_lshl_add_u64 v[234:235], s[84:85], 0, v[154:155]
	s_addc_u32 s45, s85, 0
	s_add_i32 s90, s57, s91
	global_load_lds_dwordx4 v[234:235], off
	v_lshl_add_u64 v[236:237], s[44:45], 0, v[150:151]
	s_mov_b32 m0, s90
	v_lshl_add_u64 v[238:239], s[86:87], 0, v[152:153]
	global_load_lds_dwordx4 v[236:237], off
	v_lshl_add_u64 v[236:237], s[44:45], 0, v[154:155]
	s_add_i32 m0, s90, 0x2000
	s_nop 0
	global_load_lds_dwordx4 v[236:237], off
	v_lshl_add_u64 v[236:237], s[86:87], 0, v[148:149]
	s_mov_b32 m0, s92
	s_nop 0
	global_load_lds_dwordx4 v[236:237], off
	s_mov_b32 m0, s93
	s_nop 0
	global_load_lds_dwordx4 v[238:239], off
	s_waitcnt vmcnt(8)
	s_waitcnt lgkmcnt(0)
	s_barrier
	s_setprio 1
	s_waitcnt lgkmcnt(0)
	v_mfma_f32_16x16x32_bf16 v[60:63], v[96:99], v[198:201], 0
	v_mfma_f32_16x16x32_bf16 v[56:59], v[112:115], v[198:201], 0
	v_mfma_f32_16x16x32_bf16 v[44:47], v[96:99], v[210:213], 0
	v_mfma_f32_16x16x32_bf16 v[40:43], v[112:115], v[210:213], 0
	v_mfma_f32_16x16x32_bf16 v[28:31], v[96:99], v[218:221], 0
	v_mfma_f32_16x16x32_bf16 v[24:27], v[112:115], v[218:221], 0
	v_mfma_f32_16x16x32_bf16 v[12:15], v[96:99], v[226:229], 0
	v_mfma_f32_16x16x32_bf16 v[8:11], v[112:115], v[226:229], 0
	v_mfma_f32_16x16x32_bf16 v[60:63], v[100:103], v[206:209], v[60:63]
	v_mfma_f32_16x16x32_bf16 v[56:59], v[120:123], v[206:209], v[56:59]
	v_mfma_f32_16x16x32_bf16 v[44:47], v[100:103], v[214:217], v[44:47]
	v_mfma_f32_16x16x32_bf16 v[40:43], v[120:123], v[214:217], v[40:43]
	v_mfma_f32_16x16x32_bf16 v[28:31], v[100:103], v[222:225], v[28:31]
	v_mfma_f32_16x16x32_bf16 v[24:27], v[120:123], v[222:225], v[24:27]
	v_mfma_f32_16x16x32_bf16 v[12:15], v[100:103], v[230:233], v[12:15]
	v_mfma_f32_16x16x32_bf16 v[8:11], v[120:123], v[230:233], v[8:11]
	s_setprio 0
	s_setprio 1
	v_mfma_f32_16x16x32_bf16 v[48:51], v[144:147], v[198:201], 0
	v_mfma_f32_16x16x32_bf16 v[52:55], v[186:189], v[198:201], 0
	v_mfma_f32_16x16x32_bf16 v[32:35], v[144:147], v[210:213], 0
	v_mfma_f32_16x16x32_bf16 v[36:39], v[186:189], v[210:213], 0
	v_mfma_f32_16x16x32_bf16 v[16:19], v[144:147], v[218:221], 0
	v_mfma_f32_16x16x32_bf16 v[20:23], v[186:189], v[218:221], 0
	v_mfma_f32_16x16x32_bf16 v[4:7], v[144:147], v[226:229], 0
	v_mfma_f32_16x16x32_bf16 v[0:3], v[186:189], v[226:229], 0
	v_mfma_f32_16x16x32_bf16 v[48:51], v[170:173], v[206:209], v[48:51]
	v_mfma_f32_16x16x32_bf16 v[52:55], v[190:193], v[206:209], v[52:55]
	v_mfma_f32_16x16x32_bf16 v[32:35], v[170:173], v[214:217], v[32:35]
	v_mfma_f32_16x16x32_bf16 v[36:39], v[190:193], v[214:217], v[36:39]
	v_mfma_f32_16x16x32_bf16 v[16:19], v[170:173], v[222:225], v[16:19]
	v_mfma_f32_16x16x32_bf16 v[20:23], v[190:193], v[222:225], v[20:23]
	v_mfma_f32_16x16x32_bf16 v[4:7], v[170:173], v[230:233], v[4:7]
	v_mfma_f32_16x16x32_bf16 v[0:3], v[190:193], v[230:233], v[0:3]
	s_setprio 0
	s_barrier
	s_add_i32 s90, 0, 0x18000
	s_add_i32 s33, 0, 0x1c000
	v_add_u32_e32 v120, s90, v175
	v_add_u32_e32 v190, s33, v175
	ds_read_b128 v[96:99], v120
	ds_read_b128 v[100:103], v120 offset:1024
	ds_read_b128 v[112:115], v120 offset:2048
	ds_read_b128 v[120:123], v120 offset:3072
	ds_read_b128 v[144:147], v190
	ds_read_b128 v[170:173], v190 offset:1024
	ds_read_b128 v[186:189], v190 offset:2048
	ds_read_b128 v[190:193], v190 offset:3072
	s_add_u32 s44, s86, 0x40000
	s_addc_u32 s45, s87, 0
	s_mov_b32 m0, s94
	v_lshl_add_u64 v[240:241], s[44:45], 0, v[148:149]
	ds_read_b128 v[198:201], v185 offset:32768
	ds_read_b128 v[206:209], v185 offset:33792
	ds_read_b128 v[210:213], v185 offset:34816
	ds_read_b128 v[214:217], v185 offset:35840
	ds_read_b128 v[218:221], v185 offset:36864
	ds_read_b128 v[222:225], v185 offset:37888
	ds_read_b128 v[226:229], v185 offset:38912
	ds_read_b128 v[230:233], v185 offset:39936
	global_load_lds_dwordx4 v[240:241], off
	v_lshl_add_u64 v[240:241], s[44:45], 0, v[152:153]
	s_mov_b32 m0, s95
	s_nop 0
	global_load_lds_dwordx4 v[240:241], off
	s_waitcnt vmcnt(8)
	s_waitcnt lgkmcnt(0)
	s_barrier
	s_setprio 1
	s_waitcnt lgkmcnt(0)
	v_mfma_f32_16x16x32_bf16 v[140:143], v[96:99], v[198:201], v[140:143]
	v_mfma_f32_16x16x32_bf16 v[136:139], v[112:115], v[198:201], v[136:139]
	v_mfma_f32_16x16x32_bf16 v[124:127], v[96:99], v[210:213], v[124:127]
	v_mfma_f32_16x16x32_bf16 v[116:119], v[112:115], v[210:213], v[116:119]
	v_mfma_f32_16x16x32_bf16 v[92:95], v[96:99], v[218:221], v[92:95]
	v_mfma_f32_16x16x32_bf16 v[88:91], v[112:115], v[218:221], v[88:91]
	v_mfma_f32_16x16x32_bf16 v[76:79], v[96:99], v[226:229], v[76:79]
	v_mfma_f32_16x16x32_bf16 v[72:75], v[112:115], v[226:229], v[72:75]
	v_mfma_f32_16x16x32_bf16 v[140:143], v[100:103], v[206:209], v[140:143]
	v_mfma_f32_16x16x32_bf16 v[136:139], v[120:123], v[206:209], v[136:139]
	v_mfma_f32_16x16x32_bf16 v[124:127], v[100:103], v[214:217], v[124:127]
	v_mfma_f32_16x16x32_bf16 v[116:119], v[120:123], v[214:217], v[116:119]
	v_mfma_f32_16x16x32_bf16 v[92:95], v[100:103], v[222:225], v[92:95]
	v_mfma_f32_16x16x32_bf16 v[88:91], v[120:123], v[222:225], v[88:91]
	v_mfma_f32_16x16x32_bf16 v[76:79], v[100:103], v[230:233], v[76:79]
	v_mfma_f32_16x16x32_bf16 v[72:75], v[120:123], v[230:233], v[72:75]
	s_setprio 0
	s_setprio 1
	v_mfma_f32_16x16x32_bf16 v[128:131], v[144:147], v[198:201], v[128:131]
	v_mfma_f32_16x16x32_bf16 v[132:135], v[186:189], v[198:201], v[132:135]
	v_mfma_f32_16x16x32_bf16 v[104:107], v[144:147], v[210:213], v[104:107]
	v_mfma_f32_16x16x32_bf16 v[108:111], v[186:189], v[210:213], v[108:111]
	v_mfma_f32_16x16x32_bf16 v[80:83], v[144:147], v[218:221], v[80:83]
	v_mfma_f32_16x16x32_bf16 v[84:87], v[186:189], v[218:221], v[84:87]
	v_mfma_f32_16x16x32_bf16 v[64:67], v[144:147], v[226:229], v[64:67]
	v_mfma_f32_16x16x32_bf16 v[68:71], v[186:189], v[226:229], v[68:71]
	v_mfma_f32_16x16x32_bf16 v[128:131], v[170:173], v[206:209], v[128:131]
	v_mfma_f32_16x16x32_bf16 v[132:135], v[190:193], v[206:209], v[132:135]
	v_mfma_f32_16x16x32_bf16 v[104:107], v[170:173], v[214:217], v[104:107]
	v_mfma_f32_16x16x32_bf16 v[108:111], v[190:193], v[214:217], v[108:111]
	v_mfma_f32_16x16x32_bf16 v[80:83], v[170:173], v[222:225], v[80:83]
	v_mfma_f32_16x16x32_bf16 v[84:87], v[190:193], v[222:225], v[84:87]
	v_mfma_f32_16x16x32_bf16 v[64:67], v[170:173], v[230:233], v[64:67]
	v_mfma_f32_16x16x32_bf16 v[68:71], v[190:193], v[230:233], v[68:71]
	s_setprio 0
	s_barrier
	s_add_i32 s44, s90, s91
	v_lshl_add_u64 v[194:195], v[194:195], 0, s[62:63]
	s_mov_b32 m0, s44
	ds_read_b128 v[198:201], v185 offset:49152
	ds_read_b128 v[206:209], v185 offset:50176
	ds_read_b128 v[210:213], v185 offset:51200
	ds_read_b128 v[214:217], v185 offset:52224
	ds_read_b128 v[218:221], v185 offset:53248
	ds_read_b128 v[222:225], v185 offset:54272
	ds_read_b128 v[226:229], v185 offset:55296
	ds_read_b128 v[230:233], v185 offset:56320
	global_load_lds_dwordx4 v[194:195], off
	s_add_i32 m0, s44, 0x2000
	s_add_u32 s44, s84, 0x40080
	v_lshl_add_u64 v[194:195], v[234:235], 0, s[62:63]
	s_addc_u32 s45, s85, 0
	s_add_i32 s33, s33, s91
	global_load_lds_dwordx4 v[194:195], off
	v_lshl_add_u64 v[194:195], s[44:45], 0, v[150:151]
	s_mov_b32 m0, s33
	s_nop 0
	global_load_lds_dwordx4 v[194:195], off
	v_lshl_add_u64 v[194:195], s[44:45], 0, v[154:155]
	s_add_i32 m0, s33, 0x2000
	s_nop 0
	global_load_lds_dwordx4 v[194:195], off
	v_lshl_add_u64 v[194:195], v[236:237], 0, s[62:63]
	s_mov_b32 m0, s97
	s_nop 0
	global_load_lds_dwordx4 v[194:195], off
	v_lshl_add_u64 v[194:195], v[238:239], 0, s[62:63]
	s_mov_b32 m0, s98
	s_nop 0
	global_load_lds_dwordx4 v[194:195], off
	s_waitcnt vmcnt(8)
	s_waitcnt lgkmcnt(0)
	s_barrier
	s_setprio 1
	s_waitcnt lgkmcnt(0)
	v_mfma_f32_16x16x32_bf16 v[60:63], v[96:99], v[198:201], v[60:63]
	v_mfma_f32_16x16x32_bf16 v[56:59], v[112:115], v[198:201], v[56:59]
	v_mfma_f32_16x16x32_bf16 v[44:47], v[96:99], v[210:213], v[44:47]
	v_mfma_f32_16x16x32_bf16 v[40:43], v[112:115], v[210:213], v[40:43]
	v_mfma_f32_16x16x32_bf16 v[28:31], v[96:99], v[218:221], v[28:31]
	v_mfma_f32_16x16x32_bf16 v[24:27], v[112:115], v[218:221], v[24:27]
	v_mfma_f32_16x16x32_bf16 v[12:15], v[96:99], v[226:229], v[12:15]
	v_mfma_f32_16x16x32_bf16 v[8:11], v[112:115], v[226:229], v[8:11]
	v_mfma_f32_16x16x32_bf16 v[60:63], v[100:103], v[206:209], v[60:63]
	v_mfma_f32_16x16x32_bf16 v[56:59], v[120:123], v[206:209], v[56:59]
	v_mfma_f32_16x16x32_bf16 v[44:47], v[100:103], v[214:217], v[44:47]
	v_mfma_f32_16x16x32_bf16 v[40:43], v[120:123], v[214:217], v[40:43]
	v_mfma_f32_16x16x32_bf16 v[28:31], v[100:103], v[222:225], v[28:31]
	v_mfma_f32_16x16x32_bf16 v[24:27], v[120:123], v[222:225], v[24:27]
	v_mfma_f32_16x16x32_bf16 v[12:15], v[100:103], v[230:233], v[12:15]
	v_mfma_f32_16x16x32_bf16 v[8:11], v[120:123], v[230:233], v[8:11]
	s_setprio 0
	s_setprio 1
	v_mfma_f32_16x16x32_bf16 v[48:51], v[144:147], v[198:201], v[48:51]
	v_mfma_f32_16x16x32_bf16 v[52:55], v[186:189], v[198:201], v[52:55]
	v_mfma_f32_16x16x32_bf16 v[32:35], v[144:147], v[210:213], v[32:35]
	v_mfma_f32_16x16x32_bf16 v[36:39], v[186:189], v[210:213], v[36:39]
	v_mfma_f32_16x16x32_bf16 v[16:19], v[144:147], v[218:221], v[16:19]
	v_mfma_f32_16x16x32_bf16 v[20:23], v[186:189], v[218:221], v[20:23]
	v_mfma_f32_16x16x32_bf16 v[4:7], v[144:147], v[226:229], v[4:7]
	v_mfma_f32_16x16x32_bf16 v[0:3], v[186:189], v[226:229], v[0:3]
	v_mfma_f32_16x16x32_bf16 v[48:51], v[170:173], v[206:209], v[48:51]
	v_mfma_f32_16x16x32_bf16 v[52:55], v[190:193], v[206:209], v[52:55]
	v_mfma_f32_16x16x32_bf16 v[32:35], v[170:173], v[214:217], v[32:35]
	v_mfma_f32_16x16x32_bf16 v[36:39], v[190:193], v[214:217], v[36:39]
	v_mfma_f32_16x16x32_bf16 v[16:19], v[170:173], v[222:225], v[16:19]
	v_mfma_f32_16x16x32_bf16 v[20:23], v[190:193], v[222:225], v[20:23]
	v_mfma_f32_16x16x32_bf16 v[4:7], v[170:173], v[230:233], v[4:7]
	v_mfma_f32_16x16x32_bf16 v[0:3], v[190:193], v[230:233], v[0:3]
	s_setprio 0
	s_barrier
	s_add_i32 s89, s89, 2
	s_add_u32 s0, s0, 0x100
	s_addc_u32 s1, s1, 0
	s_add_u32 s14, s14, 0x100
	s_addc_u32 s15, s15, 0
	s_cmp_gt_u32 s89, 13
	s_branch .LBB0_143

.LBB0_252:
	ds_read_b128 v[128:131], v171
	ds_read_b128 v[132:135], v171 offset:1024
	ds_read_b128 v[136:139], v171 offset:2048
	ds_read_b128 v[156:159], v171 offset:3072
	ds_read_b128 v[160:163], v172
	ds_read_b128 v[164:167], v172 offset:1024
	ds_read_b128 v[176:179], v172 offset:2048
	ds_read_b128 v[180:183], v172 offset:3072
	ds_read_b128 v[184:187], v173
	ds_read_b128 v[188:191], v173 offset:1024
	ds_read_b128 v[192:195], v173 offset:2048
	ds_read_b128 v[198:201], v173 offset:3072
	ds_read_b128 v[206:209], v173 offset:4096
	ds_read_b128 v[210:213], v173 offset:5120
	ds_read_b128 v[214:217], v173 offset:6144
	ds_read_b128 v[218:221], v173 offset:7168
	s_add_i32 s95, s95, 1
	s_mul_i32 s1, s95, s80
	s_mul_hi_u32 s10, s95, s81
	s_add_i32 s10, s10, s1
	s_mul_i32 s1, s95, s81
	s_add_u32 s18, s1, s2
	s_addc_u32 s19, s10, s3
	v_cmp_gt_i64_e32 vcc, s[18:19], v[154:155]
	v_cmp_lt_i64_e64 s[10:11], s[18:19], v[152:153]
	s_cbranch_vccnz .LBB0_258
	s_ashr_i32 s1, s18, 31
	s_lshr_b32 s1, s1, 29
	s_add_i32 s1, s18, s1
	s_and_b32 s14, s1, -8
	s_sub_i32 s14, s18, s14
	s_cmp_gt_i32 s14, -1
	s_mov_b64 s[18:19], -1
	s_cbranch_scc0 .LBB0_255
	s_lshl_b32 s15, s14, 5
	s_mov_b64 s[18:19], 0

.LBB0_258:
	s_ashr_i32 s75, s74, 31
	s_lshl_b64 s[14:15], s[74:75], 19
	s_add_u32 s76, s28, s14
	s_addc_u32 s77, s29, s15
	s_and_b64 s[14:15], s[10:11], exec
	s_cselect_b32 s1, s77, s13
	s_cselect_b32 s20, s76, s12
	s_ashr_i32 s73, s72, 31
	s_lshl_b64 s[14:15], s[72:73], 19
	s_add_u32 s78, s22, s14
	s_addc_u32 s79, s23, s15
	s_and_b64 s[14:15], s[10:11], exec
	s_cselect_b32 s21, s79, s17
	s_cselect_b32 s56, s78, s16
	s_add_u32 s12, s12, 0x40080
	s_addc_u32 s13, s13, 0
	s_add_u32 s14, s16, 0x100
	s_addc_u32 s15, s17, 0
	s_mov_b32 s57, -2
	s_waitcnt lgkmcnt(0)
	s_add_u32 s16, s12, 0xfffc0080
	s_addc_u32 s17, s13, -1
	s_cmp_eq_u32 s57, 12
	s_cselect_b32 s19, s1, s17
	s_cselect_b32 s18, s20, s16
	s_cselect_b32 s17, s21, s15
	s_cselect_b32 s16, s56, s14
	v_lshl_add_u64 v[222:223], s[12:13], 0, v[148:149]
	s_add_i32 m0, s83, 0xc000
	global_load_lds_dwordx4 v[222:223], off
	v_lshl_add_u64 v[222:223], s[12:13], 0, v[150:151]
	s_add_i32 m0, s83, 0xe000
	s_nop 0
	global_load_lds_dwordx4 v[222:223], off
	s_waitcnt vmcnt(8)
	s_waitcnt lgkmcnt(0)
	s_barrier
	s_setprio 1
	s_waitcnt lgkmcnt(0)
	v_mfma_f32_16x16x32_bf16 v[124:127], v[128:131], v[184:187], 0
	v_mfma_f32_16x16x32_bf16 v[120:123], v[136:139], v[184:187], 0
	v_mfma_f32_16x16x32_bf16 v[108:111], v[128:131], v[192:195], 0
	v_mfma_f32_16x16x32_bf16 v[104:107], v[136:139], v[192:195], 0
	v_mfma_f32_16x16x32_bf16 v[92:95], v[128:131], v[206:209], 0
	v_mfma_f32_16x16x32_bf16 v[88:91], v[136:139], v[206:209], 0
	v_mfma_f32_16x16x32_bf16 v[76:79], v[128:131], v[214:217], 0
	v_mfma_f32_16x16x32_bf16 v[72:75], v[136:139], v[214:217], 0
	v_mfma_f32_16x16x32_bf16 v[124:127], v[132:135], v[188:191], v[124:127]
	v_mfma_f32_16x16x32_bf16 v[120:123], v[156:159], v[188:191], v[120:123]
	v_mfma_f32_16x16x32_bf16 v[108:111], v[132:135], v[198:201], v[108:111]
	v_mfma_f32_16x16x32_bf16 v[104:107], v[156:159], v[198:201], v[104:107]
	v_mfma_f32_16x16x32_bf16 v[92:95], v[132:135], v[210:213], v[92:95]
	v_mfma_f32_16x16x32_bf16 v[88:91], v[156:159], v[210:213], v[88:91]
	v_mfma_f32_16x16x32_bf16 v[76:79], v[132:135], v[218:221], v[76:79]
	v_mfma_f32_16x16x32_bf16 v[72:75], v[156:159], v[218:221], v[72:75]
	s_setprio 0
	s_setprio 1
	v_mfma_f32_16x16x32_bf16 v[116:119], v[160:163], v[184:187], 0
	v_mfma_f32_16x16x32_bf16 v[112:115], v[176:179], v[184:187], 0
	v_mfma_f32_16x16x32_bf16 v[100:103], v[160:163], v[192:195], 0
	v_mfma_f32_16x16x32_bf16 v[96:99], v[176:179], v[192:195], 0
	v_mfma_f32_16x16x32_bf16 v[84:87], v[160:163], v[206:209], 0
	v_mfma_f32_16x16x32_bf16 v[80:83], v[176:179], v[206:209], 0
	v_mfma_f32_16x16x32_bf16 v[68:71], v[160:163], v[214:217], 0
	v_mfma_f32_16x16x32_bf16 v[64:67], v[176:179], v[214:217], 0
	v_mfma_f32_16x16x32_bf16 v[116:119], v[164:167], v[188:191], v[116:119]
	v_mfma_f32_16x16x32_bf16 v[112:115], v[180:183], v[188:191], v[112:115]
	v_mfma_f32_16x16x32_bf16 v[100:103], v[164:167], v[198:201], v[100:103]
	v_mfma_f32_16x16x32_bf16 v[96:99], v[180:183], v[198:201], v[96:99]
	v_mfma_f32_16x16x32_bf16 v[84:87], v[164:167], v[210:213], v[84:87]
	v_mfma_f32_16x16x32_bf16 v[80:83], v[180:183], v[210:213], v[80:83]
	v_mfma_f32_16x16x32_bf16 v[68:71], v[164:167], v[218:221], v[68:71]
	v_mfma_f32_16x16x32_bf16 v[64:67], v[180:183], v[218:221], v[64:67]
	s_setprio 0
	s_barrier
	s_add_i32 s33, s93, s82
	v_lshl_add_u64 v[222:223], s[16:17], 0, v[142:143]
	s_mov_b32 m0, s33
	ds_read_b128 v[184:187], v173 offset:16384
	ds_read_b128 v[188:191], v173 offset:17408
	ds_read_b128 v[192:195], v173 offset:18432
	ds_read_b128 v[198:201], v173 offset:19456
	ds_read_b128 v[206:209], v173 offset:20480
	ds_read_b128 v[210:213], v173 offset:21504
	ds_read_b128 v[214:217], v173 offset:22528
	ds_read_b128 v[218:221], v173 offset:23552
	global_load_lds_dwordx4 v[222:223], off
	s_add_i32 m0, s33, 0x2000
	s_add_u32 s44, s16, 0x40000
	v_lshl_add_u64 v[224:225], s[16:17], 0, v[146:147]
	s_addc_u32 s45, s17, 0
	s_add_i32 s33, s94, s82
	global_load_lds_dwordx4 v[224:225], off
	v_lshl_add_u64 v[226:227], s[44:45], 0, v[142:143]
	s_mov_b32 m0, s33
	v_lshl_add_u64 v[228:229], s[18:19], 0, v[144:145]
	global_load_lds_dwordx4 v[226:227], off
	v_lshl_add_u64 v[226:227], s[44:45], 0, v[146:147]
	s_add_i32 m0, s33, 0x2000
	s_nop 0
	global_load_lds_dwordx4 v[226:227], off
	v_lshl_add_u64 v[226:227], s[18:19], 0, v[140:141]
	s_mov_b32 m0, s83
	s_nop 0
	global_load_lds_dwordx4 v[226:227], off
	s_mov_b32 m0, s84
	s_nop 0
	global_load_lds_dwordx4 v[228:229], off
	s_waitcnt vmcnt(8)
	s_waitcnt lgkmcnt(0)
	s_barrier
	s_setprio 1
	s_waitcnt lgkmcnt(0)
	v_mfma_f32_16x16x32_bf16 v[60:63], v[128:131], v[184:187], 0
	v_mfma_f32_16x16x32_bf16 v[56:59], v[136:139], v[184:187], 0
	v_mfma_f32_16x16x32_bf16 v[44:47], v[128:131], v[192:195], 0
	v_mfma_f32_16x16x32_bf16 v[40:43], v[136:139], v[192:195], 0
	v_mfma_f32_16x16x32_bf16 v[28:31], v[128:131], v[206:209], 0
	v_mfma_f32_16x16x32_bf16 v[24:27], v[136:139], v[206:209], 0
	v_mfma_f32_16x16x32_bf16 v[12:15], v[128:131], v[214:217], 0
	v_mfma_f32_16x16x32_bf16 v[8:11], v[136:139], v[214:217], 0
	v_mfma_f32_16x16x32_bf16 v[60:63], v[132:135], v[188:191], v[60:63]
	v_mfma_f32_16x16x32_bf16 v[56:59], v[156:159], v[188:191], v[56:59]
	v_mfma_f32_16x16x32_bf16 v[44:47], v[132:135], v[198:201], v[44:47]
	v_mfma_f32_16x16x32_bf16 v[40:43], v[156:159], v[198:201], v[40:43]
	v_mfma_f32_16x16x32_bf16 v[28:31], v[132:135], v[210:213], v[28:31]
	v_mfma_f32_16x16x32_bf16 v[24:27], v[156:159], v[210:213], v[24:27]
	v_mfma_f32_16x16x32_bf16 v[12:15], v[132:135], v[218:221], v[12:15]
	v_mfma_f32_16x16x32_bf16 v[8:11], v[156:159], v[218:221], v[8:11]
	s_setprio 0
	s_setprio 1
	v_mfma_f32_16x16x32_bf16 v[52:55], v[160:163], v[184:187], 0
	v_mfma_f32_16x16x32_bf16 v[48:51], v[176:179], v[184:187], 0
	v_mfma_f32_16x16x32_bf16 v[36:39], v[160:163], v[192:195], 0
	v_mfma_f32_16x16x32_bf16 v[32:35], v[176:179], v[192:195], 0
	v_mfma_f32_16x16x32_bf16 v[20:23], v[160:163], v[206:209], 0
	v_mfma_f32_16x16x32_bf16 v[16:19], v[176:179], v[206:209], 0
	v_mfma_f32_16x16x32_bf16 v[4:7], v[160:163], v[214:217], 0
	v_mfma_f32_16x16x32_bf16 v[0:3], v[176:179], v[214:217], 0
	v_mfma_f32_16x16x32_bf16 v[52:55], v[164:167], v[188:191], v[52:55]
	v_mfma_f32_16x16x32_bf16 v[48:51], v[180:183], v[188:191], v[48:51]
	v_mfma_f32_16x16x32_bf16 v[36:39], v[164:167], v[198:201], v[36:39]
	v_mfma_f32_16x16x32_bf16 v[32:35], v[180:183], v[198:201], v[32:35]
	v_mfma_f32_16x16x32_bf16 v[20:23], v[164:167], v[210:213], v[20:23]
	v_mfma_f32_16x16x32_bf16 v[16:19], v[180:183], v[210:213], v[16:19]
	v_mfma_f32_16x16x32_bf16 v[4:7], v[164:167], v[218:221], v[4:7]
	v_mfma_f32_16x16x32_bf16 v[0:3], v[180:183], v[218:221], v[0:3]
	s_setprio 0
	s_barrier
	s_add_i32 s33, 0, 0x18000
	s_add_i32 s44, 0, 0x1c000
	v_add_u32_e32 v156, s33, v169
	v_add_u32_e32 v175, s44, v169
	ds_read_b128 v[128:131], v156
	ds_read_b128 v[132:135], v156 offset:1024
	ds_read_b128 v[136:139], v156 offset:2048
	ds_read_b128 v[156:159], v156 offset:3072
	ds_read_b128 v[160:163], v175
	ds_read_b128 v[164:167], v175 offset:1024
	ds_read_b128 v[176:179], v175 offset:2048
	ds_read_b128 v[180:183], v175 offset:3072
	s_add_u32 s18, s18, 0x40000
	s_addc_u32 s19, s19, 0
	s_mov_b32 m0, s85
	v_lshl_add_u64 v[230:231], s[18:19], 0, v[140:141]
	ds_read_b128 v[184:187], v173 offset:32768
	ds_read_b128 v[188:191], v173 offset:33792
	ds_read_b128 v[192:195], v173 offset:34816
	ds_read_b128 v[198:201], v173 offset:35840
	ds_read_b128 v[206:209], v173 offset:36864
	ds_read_b128 v[210:213], v173 offset:37888
	ds_read_b128 v[214:217], v173 offset:38912
	ds_read_b128 v[218:221], v173 offset:39936
	global_load_lds_dwordx4 v[230:231], off
	v_lshl_add_u64 v[230:231], s[18:19], 0, v[144:145]
	s_mov_b32 m0, s86
	s_nop 0
	global_load_lds_dwordx4 v[230:231], off
	s_waitcnt vmcnt(8)
	s_waitcnt lgkmcnt(0)
	s_barrier
	s_setprio 1
	s_waitcnt lgkmcnt(0)
	v_mfma_f32_16x16x32_bf16 v[124:127], v[128:131], v[184:187], v[124:127]
	v_mfma_f32_16x16x32_bf16 v[120:123], v[136:139], v[184:187], v[120:123]
	v_mfma_f32_16x16x32_bf16 v[108:111], v[128:131], v[192:195], v[108:111]
	v_mfma_f32_16x16x32_bf16 v[104:107], v[136:139], v[192:195], v[104:107]
	v_mfma_f32_16x16x32_bf16 v[92:95], v[128:131], v[206:209], v[92:95]
	v_mfma_f32_16x16x32_bf16 v[88:91], v[136:139], v[206:209], v[88:91]
	v_mfma_f32_16x16x32_bf16 v[76:79], v[128:131], v[214:217], v[76:79]
	v_mfma_f32_16x16x32_bf16 v[72:75], v[136:139], v[214:217], v[72:75]
	v_mfma_f32_16x16x32_bf16 v[124:127], v[132:135], v[188:191], v[124:127]
	v_mfma_f32_16x16x32_bf16 v[120:123], v[156:159], v[188:191], v[120:123]
	v_mfma_f32_16x16x32_bf16 v[108:111], v[132:135], v[198:201], v[108:111]
	v_mfma_f32_16x16x32_bf16 v[104:107], v[156:159], v[198:201], v[104:107]
	v_mfma_f32_16x16x32_bf16 v[92:95], v[132:135], v[210:213], v[92:95]
	v_mfma_f32_16x16x32_bf16 v[88:91], v[156:159], v[210:213], v[88:91]
	v_mfma_f32_16x16x32_bf16 v[76:79], v[132:135], v[218:221], v[76:79]
	v_mfma_f32_16x16x32_bf16 v[72:75], v[156:159], v[218:221], v[72:75]
	s_setprio 0
	s_setprio 1
	v_mfma_f32_16x16x32_bf16 v[116:119], v[160:163], v[184:187], v[116:119]
	v_mfma_f32_16x16x32_bf16 v[112:115], v[176:179], v[184:187], v[112:115]
	v_mfma_f32_16x16x32_bf16 v[100:103], v[160:163], v[192:195], v[100:103]
	v_mfma_f32_16x16x32_bf16 v[96:99], v[176:179], v[192:195], v[96:99]
	v_mfma_f32_16x16x32_bf16 v[84:87], v[160:163], v[206:209], v[84:87]
	v_mfma_f32_16x16x32_bf16 v[80:83], v[176:179], v[206:209], v[80:83]
	v_mfma_f32_16x16x32_bf16 v[68:71], v[160:163], v[214:217], v[68:71]
	v_mfma_f32_16x16x32_bf16 v[64:67], v[176:179], v[214:217], v[64:67]
	v_mfma_f32_16x16x32_bf16 v[116:119], v[164:167], v[188:191], v[116:119]
	v_mfma_f32_16x16x32_bf16 v[112:115], v[180:183], v[188:191], v[112:115]
	v_mfma_f32_16x16x32_bf16 v[100:103], v[164:167], v[198:201], v[100:103]
	v_mfma_f32_16x16x32_bf16 v[96:99], v[180:183], v[198:201], v[96:99]
	v_mfma_f32_16x16x32_bf16 v[84:87], v[164:167], v[210:213], v[84:87]
	v_mfma_f32_16x16x32_bf16 v[80:83], v[180:183], v[210:213], v[80:83]
	v_mfma_f32_16x16x32_bf16 v[68:71], v[164:167], v[218:221], v[68:71]
	v_mfma_f32_16x16x32_bf16 v[64:67], v[180:183], v[218:221], v[64:67]
	s_setprio 0
	s_barrier
	s_add_i32 s18, s33, s82
	v_lshl_add_u64 v[222:223], v[222:223], 0, s[68:69]
	s_mov_b32 m0, s18
	ds_read_b128 v[184:187], v173 offset:49152
	ds_read_b128 v[188:191], v173 offset:50176
	ds_read_b128 v[192:195], v173 offset:51200
	ds_read_b128 v[198:201], v173 offset:52224
	ds_read_b128 v[206:209], v173 offset:53248
	ds_read_b128 v[210:213], v173 offset:54272
	ds_read_b128 v[214:217], v173 offset:55296
	ds_read_b128 v[218:221], v173 offset:56320
	global_load_lds_dwordx4 v[222:223], off
	s_add_i32 m0, s18, 0x2000
	s_add_u32 s16, s16, 0x40080
	v_lshl_add_u64 v[222:223], v[224:225], 0, s[68:69]
	s_addc_u32 s17, s17, 0
	s_add_i32 s18, s44, s82
	global_load_lds_dwordx4 v[222:223], off
	v_lshl_add_u64 v[222:223], s[16:17], 0, v[142:143]
	s_mov_b32 m0, s18
	s_nop 0
	global_load_lds_dwordx4 v[222:223], off
	v_lshl_add_u64 v[222:223], s[16:17], 0, v[146:147]
	s_add_i32 m0, s18, 0x2000
	s_nop 0
	global_load_lds_dwordx4 v[222:223], off
	v_lshl_add_u64 v[222:223], v[226:227], 0, s[68:69]
	s_mov_b32 m0, s91
	s_nop 0
	global_load_lds_dwordx4 v[222:223], off
	v_lshl_add_u64 v[222:223], v[228:229], 0, s[68:69]
	s_mov_b32 m0, s92
	s_nop 0
	global_load_lds_dwordx4 v[222:223], off
	s_waitcnt vmcnt(8)
	s_waitcnt lgkmcnt(0)
	s_barrier
	s_setprio 1
	s_waitcnt lgkmcnt(0)
	v_mfma_f32_16x16x32_bf16 v[60:63], v[128:131], v[184:187], v[60:63]
	v_mfma_f32_16x16x32_bf16 v[56:59], v[136:139], v[184:187], v[56:59]
	v_mfma_f32_16x16x32_bf16 v[44:47], v[128:131], v[192:195], v[44:47]
	v_mfma_f32_16x16x32_bf16 v[40:43], v[136:139], v[192:195], v[40:43]
	v_mfma_f32_16x16x32_bf16 v[28:31], v[128:131], v[206:209], v[28:31]
	v_mfma_f32_16x16x32_bf16 v[24:27], v[136:139], v[206:209], v[24:27]
	v_mfma_f32_16x16x32_bf16 v[12:15], v[128:131], v[214:217], v[12:15]
	v_mfma_f32_16x16x32_bf16 v[8:11], v[136:139], v[214:217], v[8:11]
	v_mfma_f32_16x16x32_bf16 v[60:63], v[132:135], v[188:191], v[60:63]
	v_mfma_f32_16x16x32_bf16 v[56:59], v[156:159], v[188:191], v[56:59]
	v_mfma_f32_16x16x32_bf16 v[44:47], v[132:135], v[198:201], v[44:47]
	v_mfma_f32_16x16x32_bf16 v[40:43], v[156:159], v[198:201], v[40:43]
	v_mfma_f32_16x16x32_bf16 v[28:31], v[132:135], v[210:213], v[28:31]
	v_mfma_f32_16x16x32_bf16 v[24:27], v[156:159], v[210:213], v[24:27]
	v_mfma_f32_16x16x32_bf16 v[12:15], v[132:135], v[218:221], v[12:15]
	v_mfma_f32_16x16x32_bf16 v[8:11], v[156:159], v[218:221], v[8:11]
	s_setprio 0
	s_setprio 1
	v_mfma_f32_16x16x32_bf16 v[52:55], v[160:163], v[184:187], v[52:55]
	v_mfma_f32_16x16x32_bf16 v[48:51], v[176:179], v[184:187], v[48:51]
	v_mfma_f32_16x16x32_bf16 v[36:39], v[160:163], v[192:195], v[36:39]
	v_mfma_f32_16x16x32_bf16 v[32:35], v[176:179], v[192:195], v[32:35]
	v_mfma_f32_16x16x32_bf16 v[20:23], v[160:163], v[206:209], v[20:23]
	v_mfma_f32_16x16x32_bf16 v[16:19], v[176:179], v[206:209], v[16:19]
	v_mfma_f32_16x16x32_bf16 v[4:7], v[160:163], v[214:217], v[4:7]
	v_mfma_f32_16x16x32_bf16 v[0:3], v[176:179], v[214:217], v[0:3]
	v_mfma_f32_16x16x32_bf16 v[52:55], v[164:167], v[188:191], v[52:55]
	v_mfma_f32_16x16x32_bf16 v[48:51], v[180:183], v[188:191], v[48:51]
	v_mfma_f32_16x16x32_bf16 v[36:39], v[164:167], v[198:201], v[36:39]
	v_mfma_f32_16x16x32_bf16 v[32:35], v[180:183], v[198:201], v[32:35]
	v_mfma_f32_16x16x32_bf16 v[20:23], v[164:167], v[210:213], v[20:23]
	v_mfma_f32_16x16x32_bf16 v[16:19], v[180:183], v[210:213], v[16:19]
	v_mfma_f32_16x16x32_bf16 v[4:7], v[164:167], v[218:221], v[4:7]
	v_mfma_f32_16x16x32_bf16 v[0:3], v[180:183], v[218:221], v[0:3]
	s_setprio 0
	s_barrier
	s_add_i32 s57, s57, 2
	s_add_u32 s12, s12, 0x100
	s_addc_u32 s13, s13, 0
	s_add_u32 s14, s14, 0x100
	s_addc_u32 s15, s15, 0
	s_cmp_gt_u32 s57, 13
	s_branch .LBB0_259

.LBB0_367:
	ds_read_b128 v[32:35], v208
	ds_read_b128 v[36:39], v208 offset:1024
	ds_read_b128 v[40:43], v208 offset:2048
	ds_read_b128 v[44:47], v208 offset:3072
	ds_read_b128 v[144:147], v209
	ds_read_b128 v[148:151], v209 offset:1024
	ds_read_b128 v[152:155], v209 offset:2048
	ds_read_b128 v[156:159], v209 offset:3072
	ds_read_b128 v[182:185], v210
	ds_read_b128 v[186:189], v210 offset:1024
	ds_read_b128 v[190:193], v210 offset:2048
	ds_read_b128 v[198:201], v210 offset:3072
	ds_read_b128 v[214:217], v210 offset:4096
	ds_read_b128 v[218:221], v210 offset:5120
	ds_read_b128 v[222:225], v210 offset:6144
	ds_read_b128 v[226:229], v210 offset:7168
	s_add_i32 s83, s83, 1
	s_mul_i32 s8, s83, s80
	s_mul_hi_u32 s9, s83, s81
	s_add_i32 s9, s9, s8
	s_mul_i32 s8, s83, s81
	s_add_u32 s64, s8, s2
	s_addc_u32 s65, s9, s3
	v_cmp_gt_i64_e32 vcc, s[64:65], v[180:181]
	v_cmp_lt_i64_e64 s[8:9], s[64:65], v[178:179]
	s_cbranch_vccnz .LBB0_373
	s_ashr_i32 s11, s64, 31
	s_lshr_b32 s11, s11, 29
	s_add_i32 s11, s64, s11
	s_and_b32 s13, s11, -8
	s_sub_i32 s13, s64, s13
	s_cmp_gt_i32 s13, -1
	s_mov_b64 s[20:21], -1
	s_cbranch_scc0 .LBB0_370
	s_lshl_b32 s14, s13, 7
	s_mov_b64 s[20:21], 0

.LBB0_373:
	s_ashr_i32 s23, s22, 31
	s_lshl_b64 s[14:15], s[22:23], 19
	s_add_u32 s64, s36, s14
	s_addc_u32 s65, s37, s15
	s_and_b64 s[14:15], s[8:9], exec
	s_cselect_b32 s11, s65, s69
	s_cselect_b32 s13, s64, s68
	s_ashr_i32 s21, s20, 31
	s_lshl_b64 s[14:15], s[20:21], 19
	s_add_u32 s66, s58, s14
	s_addc_u32 s67, s59, s15
	s_and_b64 s[14:15], s[8:9], exec
	s_cselect_b32 s21, s67, s71
	s_cselect_b32 s23, s66, s70
	s_add_u32 s68, s68, 0x40080
	s_addc_u32 s69, s69, 0
	s_add_u32 s14, s70, 0x100
	s_addc_u32 s15, s71, 0
	s_mov_b32 s56, -2
	s_add_u32 s33, s68, 0xfffc0080
	s_addc_u32 s57, s69, -1
	s_cmp_eq_u32 s56, 12
	s_cselect_b32 s73, s11, s57
	s_cselect_b32 s72, s13, s33
	s_cselect_b32 s71, s21, s15
	s_cselect_b32 s70, s23, s14
	v_lshl_add_u64 v[194:195], s[68:69], 0, v[174:175]
	s_add_i32 m0, s77, 0xc000
	global_load_lds_dwordx4 v[194:195], off
	v_lshl_add_u64 v[194:195], s[68:69], 0, v[176:177]
	s_add_i32 m0, s77, 0xe000
	s_nop 0
	global_load_lds_dwordx4 v[194:195], off
	s_waitcnt vmcnt(8)
	s_waitcnt lgkmcnt(0)
	s_barrier
	s_setprio 1
	s_waitcnt lgkmcnt(0)
	v_mfma_f32_16x16x32_bf16 v[140:143], v[32:35], v[182:185], 0
	v_mfma_f32_16x16x32_bf16 v[136:139], v[40:43], v[182:185], 0
	v_mfma_f32_16x16x32_bf16 v[124:127], v[32:35], v[190:193], 0
	v_mfma_f32_16x16x32_bf16 v[120:123], v[40:43], v[190:193], 0
	v_mfma_f32_16x16x32_bf16 v[108:111], v[32:35], v[214:217], 0
	v_mfma_f32_16x16x32_bf16 v[104:107], v[40:43], v[214:217], 0
	v_mfma_f32_16x16x32_bf16 v[92:95], v[32:35], v[222:225], 0
	v_mfma_f32_16x16x32_bf16 v[88:91], v[40:43], v[222:225], 0
	v_mfma_f32_16x16x32_bf16 v[140:143], v[36:39], v[186:189], v[140:143]
	v_mfma_f32_16x16x32_bf16 v[136:139], v[44:47], v[186:189], v[136:139]
	v_mfma_f32_16x16x32_bf16 v[124:127], v[36:39], v[198:201], v[124:127]
	v_mfma_f32_16x16x32_bf16 v[120:123], v[44:47], v[198:201], v[120:123]
	v_mfma_f32_16x16x32_bf16 v[108:111], v[36:39], v[218:221], v[108:111]
	v_mfma_f32_16x16x32_bf16 v[104:107], v[44:47], v[218:221], v[104:107]
	v_mfma_f32_16x16x32_bf16 v[92:95], v[36:39], v[226:229], v[92:95]
	v_mfma_f32_16x16x32_bf16 v[88:91], v[44:47], v[226:229], v[88:91]
	s_setprio 0
	s_setprio 1
	v_mfma_f32_16x16x32_bf16 v[132:135], v[144:147], v[182:185], 0
	v_mfma_f32_16x16x32_bf16 v[128:131], v[152:155], v[182:185], 0
	v_mfma_f32_16x16x32_bf16 v[116:119], v[144:147], v[190:193], 0
	v_mfma_f32_16x16x32_bf16 v[112:115], v[152:155], v[190:193], 0
	v_mfma_f32_16x16x32_bf16 v[100:103], v[144:147], v[214:217], 0
	v_mfma_f32_16x16x32_bf16 v[96:99], v[152:155], v[214:217], 0
	v_mfma_f32_16x16x32_bf16 v[84:87], v[144:147], v[222:225], 0
	v_mfma_f32_16x16x32_bf16 v[80:83], v[152:155], v[222:225], 0
	v_mfma_f32_16x16x32_bf16 v[132:135], v[148:151], v[186:189], v[132:135]
	v_mfma_f32_16x16x32_bf16 v[128:131], v[156:159], v[186:189], v[128:131]
	v_mfma_f32_16x16x32_bf16 v[116:119], v[148:151], v[198:201], v[116:119]
	v_mfma_f32_16x16x32_bf16 v[112:115], v[156:159], v[198:201], v[112:115]
	v_mfma_f32_16x16x32_bf16 v[100:103], v[148:151], v[218:221], v[100:103]
	v_mfma_f32_16x16x32_bf16 v[96:99], v[156:159], v[218:221], v[96:99]
	v_mfma_f32_16x16x32_bf16 v[84:87], v[148:151], v[226:229], v[84:87]
	v_mfma_f32_16x16x32_bf16 v[80:83], v[156:159], v[226:229], v[80:83]
	s_setprio 0
	s_barrier
	s_add_i32 s33, s87, s76
	v_lshl_add_u64 v[194:195], s[70:71], 0, v[162:163]
	s_mov_b32 m0, s33
	ds_read_b128 v[182:185], v210 offset:16384
	ds_read_b128 v[186:189], v210 offset:17408
	ds_read_b128 v[190:193], v210 offset:18432
	ds_read_b128 v[198:201], v210 offset:19456
	ds_read_b128 v[214:217], v210 offset:20480
	ds_read_b128 v[218:221], v210 offset:21504
	ds_read_b128 v[222:225], v210 offset:22528
	ds_read_b128 v[226:229], v210 offset:23552
	global_load_lds_dwordx4 v[194:195], off
	s_add_i32 m0, s33, 0x2000
	s_add_u32 s88, s70, 0x40000
	v_lshl_add_u64 v[230:231], s[70:71], 0, v[166:167]
	s_addc_u32 s89, s71, 0
	s_add_i32 s33, s91, s76
	global_load_lds_dwordx4 v[230:231], off
	v_lshl_add_u64 v[232:233], s[88:89], 0, v[162:163]
	s_mov_b32 m0, s33
	v_lshl_add_u64 v[234:235], s[72:73], 0, v[164:165]
	global_load_lds_dwordx4 v[232:233], off
	v_lshl_add_u64 v[232:233], s[88:89], 0, v[166:167]
	s_add_i32 m0, s33, 0x2000
	s_nop 0
	global_load_lds_dwordx4 v[232:233], off
	v_lshl_add_u64 v[232:233], s[72:73], 0, v[160:161]
	s_mov_b32 m0, s77
	s_nop 0
	global_load_lds_dwordx4 v[232:233], off
	s_mov_b32 m0, s78
	s_nop 0
	global_load_lds_dwordx4 v[234:235], off
	s_waitcnt vmcnt(8)
	s_waitcnt lgkmcnt(0)
	s_barrier
	s_setprio 1
	s_waitcnt lgkmcnt(0)
	v_mfma_f32_16x16x32_bf16 v[76:79], v[32:35], v[182:185], 0
	v_mfma_f32_16x16x32_bf16 v[72:75], v[40:43], v[182:185], 0
	v_mfma_f32_16x16x32_bf16 v[60:63], v[32:35], v[190:193], 0
	v_mfma_f32_16x16x32_bf16 v[56:59], v[40:43], v[190:193], 0
	v_mfma_f32_16x16x32_bf16 v[28:31], v[32:35], v[214:217], 0
	v_mfma_f32_16x16x32_bf16 v[24:27], v[40:43], v[214:217], 0
	v_mfma_f32_16x16x32_bf16 v[12:15], v[32:35], v[222:225], 0
	v_mfma_f32_16x16x32_bf16 v[8:11], v[40:43], v[222:225], 0
	v_mfma_f32_16x16x32_bf16 v[76:79], v[36:39], v[186:189], v[76:79]
	v_mfma_f32_16x16x32_bf16 v[72:75], v[44:47], v[186:189], v[72:75]
	v_mfma_f32_16x16x32_bf16 v[60:63], v[36:39], v[198:201], v[60:63]
	v_mfma_f32_16x16x32_bf16 v[56:59], v[44:47], v[198:201], v[56:59]
	v_mfma_f32_16x16x32_bf16 v[28:31], v[36:39], v[218:221], v[28:31]
	v_mfma_f32_16x16x32_bf16 v[24:27], v[44:47], v[218:221], v[24:27]
	v_mfma_f32_16x16x32_bf16 v[12:15], v[36:39], v[226:229], v[12:15]
	v_mfma_f32_16x16x32_bf16 v[8:11], v[44:47], v[226:229], v[8:11]
	s_setprio 0
	s_setprio 1
	v_mfma_f32_16x16x32_bf16 v[20:23], v[144:147], v[214:217], 0
	v_mfma_f32_16x16x32_bf16 v[16:19], v[152:155], v[214:217], 0
	v_mfma_f32_16x16x32_bf16 v[4:7], v[144:147], v[222:225], 0
	v_mfma_f32_16x16x32_bf16 v[0:3], v[152:155], v[222:225], 0
	v_mfma_f32_16x16x32_bf16 v[32:35], v[144:147], v[182:185], 0
	v_mfma_f32_16x16x32_bf16 v[36:39], v[152:155], v[182:185], 0
	v_mfma_f32_16x16x32_bf16 v[40:43], v[144:147], v[190:193], 0
	v_mfma_f32_16x16x32_bf16 v[44:47], v[152:155], v[190:193], 0
	v_mfma_f32_16x16x32_bf16 v[20:23], v[148:151], v[218:221], v[20:23]
	v_mfma_f32_16x16x32_bf16 v[16:19], v[156:159], v[218:221], v[16:19]
	v_mfma_f32_16x16x32_bf16 v[4:7], v[148:151], v[226:229], v[4:7]
	v_mfma_f32_16x16x32_bf16 v[0:3], v[156:159], v[226:229], v[0:3]
	v_mfma_f32_16x16x32_bf16 v[32:35], v[148:151], v[186:189], v[32:35]
	v_mfma_f32_16x16x32_bf16 v[36:39], v[156:159], v[186:189], v[36:39]
	v_mfma_f32_16x16x32_bf16 v[40:43], v[148:151], v[198:201], v[40:43]
	v_mfma_f32_16x16x32_bf16 v[44:47], v[156:159], v[198:201], v[44:47]
	s_setprio 0
	s_barrier
	s_add_i32 s33, 0, 0x18000
	s_add_i32 s57, 0, 0x1c000
	v_add_u32_e32 v68, s33, v207
	v_add_u32_e32 v156, s57, v207
	ds_read_b128 v[48:51], v68
	ds_read_b128 v[52:55], v68 offset:1024
	ds_read_b128 v[64:67], v68 offset:2048
	ds_read_b128 v[68:71], v68 offset:3072
	ds_read_b128 v[144:147], v156
	ds_read_b128 v[148:151], v156 offset:1024
	ds_read_b128 v[152:155], v156 offset:2048
	ds_read_b128 v[156:159], v156 offset:3072
	s_add_u32 s72, s72, 0x40000
	s_addc_u32 s73, s73, 0
	s_mov_b32 m0, s79
	v_lshl_add_u64 v[236:237], s[72:73], 0, v[160:161]
	ds_read_b128 v[182:185], v210 offset:32768
	ds_read_b128 v[186:189], v210 offset:33792
	ds_read_b128 v[190:193], v210 offset:34816
	ds_read_b128 v[198:201], v210 offset:35840
	ds_read_b128 v[214:217], v210 offset:36864
	ds_read_b128 v[218:221], v210 offset:37888
	ds_read_b128 v[222:225], v210 offset:38912
	ds_read_b128 v[226:229], v210 offset:39936
	global_load_lds_dwordx4 v[236:237], off
	v_lshl_add_u64 v[236:237], s[72:73], 0, v[164:165]
	s_mov_b32 m0, s82
	s_nop 0
	global_load_lds_dwordx4 v[236:237], off
	s_waitcnt vmcnt(8)
	s_waitcnt lgkmcnt(0)
	s_barrier
	s_setprio 1
	s_waitcnt lgkmcnt(0)
	v_mfma_f32_16x16x32_bf16 v[140:143], v[48:51], v[182:185], v[140:143]
	v_mfma_f32_16x16x32_bf16 v[136:139], v[64:67], v[182:185], v[136:139]
	v_mfma_f32_16x16x32_bf16 v[124:127], v[48:51], v[190:193], v[124:127]
	v_mfma_f32_16x16x32_bf16 v[120:123], v[64:67], v[190:193], v[120:123]
	v_mfma_f32_16x16x32_bf16 v[108:111], v[48:51], v[214:217], v[108:111]
	v_mfma_f32_16x16x32_bf16 v[104:107], v[64:67], v[214:217], v[104:107]
	v_mfma_f32_16x16x32_bf16 v[92:95], v[48:51], v[222:225], v[92:95]
	v_mfma_f32_16x16x32_bf16 v[88:91], v[64:67], v[222:225], v[88:91]
	v_mfma_f32_16x16x32_bf16 v[140:143], v[52:55], v[186:189], v[140:143]
	v_mfma_f32_16x16x32_bf16 v[136:139], v[68:71], v[186:189], v[136:139]
	v_mfma_f32_16x16x32_bf16 v[124:127], v[52:55], v[198:201], v[124:127]
	v_mfma_f32_16x16x32_bf16 v[120:123], v[68:71], v[198:201], v[120:123]
	v_mfma_f32_16x16x32_bf16 v[108:111], v[52:55], v[218:221], v[108:111]
	v_mfma_f32_16x16x32_bf16 v[104:107], v[68:71], v[218:221], v[104:107]
	v_mfma_f32_16x16x32_bf16 v[92:95], v[52:55], v[226:229], v[92:95]
	v_mfma_f32_16x16x32_bf16 v[88:91], v[68:71], v[226:229], v[88:91]
	s_setprio 0
	s_setprio 1
	v_mfma_f32_16x16x32_bf16 v[132:135], v[144:147], v[182:185], v[132:135]
	v_mfma_f32_16x16x32_bf16 v[128:131], v[152:155], v[182:185], v[128:131]
	v_mfma_f32_16x16x32_bf16 v[116:119], v[144:147], v[190:193], v[116:119]
	v_mfma_f32_16x16x32_bf16 v[112:115], v[152:155], v[190:193], v[112:115]
	v_mfma_f32_16x16x32_bf16 v[100:103], v[144:147], v[214:217], v[100:103]
	v_mfma_f32_16x16x32_bf16 v[96:99], v[152:155], v[214:217], v[96:99]
	v_mfma_f32_16x16x32_bf16 v[84:87], v[144:147], v[222:225], v[84:87]
	v_mfma_f32_16x16x32_bf16 v[80:83], v[152:155], v[222:225], v[80:83]
	v_mfma_f32_16x16x32_bf16 v[132:135], v[148:151], v[186:189], v[132:135]
	v_mfma_f32_16x16x32_bf16 v[128:131], v[156:159], v[186:189], v[128:131]
	v_mfma_f32_16x16x32_bf16 v[116:119], v[148:151], v[198:201], v[116:119]
	v_mfma_f32_16x16x32_bf16 v[112:115], v[156:159], v[198:201], v[112:115]
	v_mfma_f32_16x16x32_bf16 v[100:103], v[148:151], v[218:221], v[100:103]
	v_mfma_f32_16x16x32_bf16 v[96:99], v[156:159], v[218:221], v[96:99]
	v_mfma_f32_16x16x32_bf16 v[84:87], v[148:151], v[226:229], v[84:87]
	v_mfma_f32_16x16x32_bf16 v[80:83], v[156:159], v[226:229], v[80:83]
	s_setprio 0
	s_barrier
	s_add_i32 s33, s33, s76
	v_lshl_add_u64 v[194:195], v[194:195], 0, s[16:17]
	s_mov_b32 m0, s33
	ds_read_b128 v[182:185], v210 offset:49152
	ds_read_b128 v[186:189], v210 offset:50176
	ds_read_b128 v[190:193], v210 offset:51200
	ds_read_b128 v[198:201], v210 offset:52224
	ds_read_b128 v[214:217], v210 offset:53248
	ds_read_b128 v[218:221], v210 offset:54272
	ds_read_b128 v[222:225], v210 offset:55296
	ds_read_b128 v[226:229], v210 offset:56320
	global_load_lds_dwordx4 v[194:195], off
	s_add_i32 m0, s33, 0x2000
	s_add_u32 s70, s70, 0x40080
	v_lshl_add_u64 v[194:195], v[230:231], 0, s[16:17]
	s_addc_u32 s71, s71, 0
	s_add_i32 s33, s57, s76
	global_load_lds_dwordx4 v[194:195], off
	v_lshl_add_u64 v[194:195], s[70:71], 0, v[162:163]
	s_mov_b32 m0, s33
	s_nop 0
	global_load_lds_dwordx4 v[194:195], off
	v_lshl_add_u64 v[194:195], s[70:71], 0, v[166:167]
	s_add_i32 m0, s33, 0x2000
	s_nop 0
	global_load_lds_dwordx4 v[194:195], off
	v_lshl_add_u64 v[194:195], v[232:233], 0, s[16:17]
	s_mov_b32 m0, s85
	s_nop 0
	global_load_lds_dwordx4 v[194:195], off
	v_lshl_add_u64 v[194:195], v[234:235], 0, s[16:17]
	s_mov_b32 m0, s86
	s_nop 0
	global_load_lds_dwordx4 v[194:195], off
	s_waitcnt vmcnt(8)
	s_waitcnt lgkmcnt(0)
	s_barrier
	s_setprio 1
	s_waitcnt lgkmcnt(0)
	v_mfma_f32_16x16x32_bf16 v[76:79], v[48:51], v[182:185], v[76:79]
	v_mfma_f32_16x16x32_bf16 v[72:75], v[64:67], v[182:185], v[72:75]
	v_mfma_f32_16x16x32_bf16 v[60:63], v[48:51], v[190:193], v[60:63]
	v_mfma_f32_16x16x32_bf16 v[56:59], v[64:67], v[190:193], v[56:59]
	v_mfma_f32_16x16x32_bf16 v[28:31], v[48:51], v[214:217], v[28:31]
	v_mfma_f32_16x16x32_bf16 v[24:27], v[64:67], v[214:217], v[24:27]
	v_mfma_f32_16x16x32_bf16 v[12:15], v[48:51], v[222:225], v[12:15]
	v_mfma_f32_16x16x32_bf16 v[8:11], v[64:67], v[222:225], v[8:11]
	v_mfma_f32_16x16x32_bf16 v[76:79], v[52:55], v[186:189], v[76:79]
	v_mfma_f32_16x16x32_bf16 v[72:75], v[68:71], v[186:189], v[72:75]
	v_mfma_f32_16x16x32_bf16 v[60:63], v[52:55], v[198:201], v[60:63]
	v_mfma_f32_16x16x32_bf16 v[56:59], v[68:71], v[198:201], v[56:59]
	v_mfma_f32_16x16x32_bf16 v[28:31], v[52:55], v[218:221], v[28:31]
	v_mfma_f32_16x16x32_bf16 v[24:27], v[68:71], v[218:221], v[24:27]
	v_mfma_f32_16x16x32_bf16 v[12:15], v[52:55], v[226:229], v[12:15]
	v_mfma_f32_16x16x32_bf16 v[8:11], v[68:71], v[226:229], v[8:11]
	s_setprio 0
	s_setprio 1
	v_mfma_f32_16x16x32_bf16 v[32:35], v[144:147], v[182:185], v[32:35]
	v_mfma_f32_16x16x32_bf16 v[68:71], v[148:151], v[186:189], v[32:35]
	v_mfma_f32_16x16x32_bf16 v[32:35], v[152:155], v[182:185], v[36:39]
	v_mfma_f32_16x16x32_bf16 v[64:67], v[156:159], v[186:189], v[32:35]
	v_mfma_f32_16x16x32_bf16 v[32:35], v[144:147], v[190:193], v[40:43]
	v_mfma_f32_16x16x32_bf16 v[52:55], v[148:151], v[198:201], v[32:35]
	v_mfma_f32_16x16x32_bf16 v[32:35], v[152:155], v[190:193], v[44:47]
	v_mfma_f32_16x16x32_bf16 v[20:23], v[144:147], v[214:217], v[20:23]
	v_mfma_f32_16x16x32_bf16 v[16:19], v[152:155], v[214:217], v[16:19]
	v_mfma_f32_16x16x32_bf16 v[4:7], v[144:147], v[222:225], v[4:7]
	v_mfma_f32_16x16x32_bf16 v[0:3], v[152:155], v[222:225], v[0:3]
	v_mfma_f32_16x16x32_bf16 v[48:51], v[156:159], v[198:201], v[32:35]
	v_mfma_f32_16x16x32_bf16 v[20:23], v[148:151], v[218:221], v[20:23]
	v_mfma_f32_16x16x32_bf16 v[16:19], v[156:159], v[218:221], v[16:19]
	v_mfma_f32_16x16x32_bf16 v[4:7], v[148:151], v[226:229], v[4:7]
	v_mfma_f32_16x16x32_bf16 v[0:3], v[156:159], v[226:229], v[0:3]
	s_setprio 0
	s_barrier
	s_add_i32 s56, s56, 2
	s_add_u32 s68, s68, 0x100
	s_addc_u32 s69, s69, 0
	s_add_u32 s14, s14, 0x100
	s_addc_u32 s15, s15, 0
	s_cmp_gt_u32 s56, 13
	s_branch .LBB0_374

.LBB0_751:
	ds_read_b128 v[144:147], v153
	ds_read_b128 v[156:159], v153 offset:1024
	ds_read_b128 v[160:163], v153 offset:2048
	ds_read_b128 v[164:167], v153 offset:3072
	ds_read_b128 v[168:171], v154
	ds_read_b128 v[172:175], v154 offset:1024
	ds_read_b128 v[176:179], v154 offset:2048
	ds_read_b128 v[180:183], v154 offset:3072
	ds_read_b128 v[184:187], v155
	ds_read_b128 v[188:191], v155 offset:1024
	ds_read_b128 v[192:195], v155 offset:2048
	ds_read_b128 v[196:199], v155 offset:3072
	ds_read_b128 v[200:203], v155 offset:4096
	ds_read_b128 v[204:207], v155 offset:5120
	ds_read_b128 v[208:211], v155 offset:6144
	ds_read_b128 v[212:215], v155 offset:7168
	s_add_i32 s47, s47, 1
	s_mul_i32 s0, s47, s80
	s_mul_hi_u32 s1, s47, s81
	s_add_i32 s1, s1, s0
	s_mul_i32 s0, s47, s81
	s_add_u32 s22, s0, s2
	s_addc_u32 s23, s1, s3
	v_cmp_gt_i64_e32 vcc, s[22:23], v[142:143]
	v_cmp_lt_i64_e64 s[0:1], s[22:23], v[140:141]
	s_cbranch_vccnz .LBB0_757
	s_ashr_i32 s18, s22, 31
	s_lshr_b32 s18, s18, 29
	s_add_i32 s20, s22, s18
	s_and_b32 s18, s20, -8
	s_sub_i32 s21, s22, s18
	s_cmp_gt_i32 s21, -1
	s_mov_b64 s[18:19], -1
	s_cbranch_scc0 .LBB0_754
	s_lshl_b32 s22, s21, 5
	s_mov_b64 s[18:19], 0

.LBB0_757:
	s_ashr_i32 s21, s20, 31
	s_lshl_b64 s[22:23], s[20:21], 19
	s_add_u32 s22, s28, s22
	s_addc_u32 s23, s29, s23
	s_and_b64 s[24:25], s[0:1], exec
	s_cselect_b32 s21, s23, s39
	s_cselect_b32 s53, s22, s38
	s_ashr_i32 s19, s18, 31
	s_lshl_b64 s[24:25], s[18:19], 19
	s_add_u32 s24, s34, s24
	s_addc_u32 s25, s35, s25
	s_and_b64 s[42:43], s[0:1], exec
	s_cselect_b32 s19, s25, s41
	s_cselect_b32 s54, s24, s40
	s_add_u32 s38, s38, 0x40080
	s_addc_u32 s39, s39, 0
	s_add_u32 s55, s40, 0x100
	s_addc_u32 s56, s41, 0
	s_mov_b32 s57, -2
	s_add_u32 s40, s38, 0xfffc0080
	s_addc_u32 s41, s39, -1
	s_cmp_eq_u32 s57, 12
	s_cselect_b32 s43, s21, s41
	s_cselect_b32 s42, s53, s40
	s_cselect_b32 s41, s19, s56
	s_cselect_b32 s40, s54, s55
	v_lshl_add_u64 v[148:149], s[38:39], 0, v[136:137]
	s_add_i32 m0, s27, 0xc000
	global_load_lds_dwordx4 v[148:149], off
	v_lshl_add_u64 v[148:149], s[38:39], 0, v[138:139]
	s_add_i32 m0, s27, 0xe000
	s_nop 0
	global_load_lds_dwordx4 v[148:149], off
	s_waitcnt vmcnt(8)
	s_waitcnt lgkmcnt(0)
	s_barrier
	s_setprio 1
	s_waitcnt lgkmcnt(0)
	v_mfma_f32_16x16x32_bf16 v[124:127], v[144:147], v[184:187], 0
	v_mfma_f32_16x16x32_bf16 v[120:123], v[160:163], v[184:187], 0
	v_mfma_f32_16x16x32_bf16 v[108:111], v[144:147], v[192:195], 0
	v_mfma_f32_16x16x32_bf16 v[104:107], v[160:163], v[192:195], 0
	v_mfma_f32_16x16x32_bf16 v[92:95], v[144:147], v[200:203], 0
	v_mfma_f32_16x16x32_bf16 v[88:91], v[160:163], v[200:203], 0
	v_mfma_f32_16x16x32_bf16 v[76:79], v[144:147], v[208:211], 0
	v_mfma_f32_16x16x32_bf16 v[72:75], v[160:163], v[208:211], 0
	v_mfma_f32_16x16x32_bf16 v[124:127], v[156:159], v[188:191], v[124:127]
	v_mfma_f32_16x16x32_bf16 v[120:123], v[164:167], v[188:191], v[120:123]
	v_mfma_f32_16x16x32_bf16 v[108:111], v[156:159], v[196:199], v[108:111]
	v_mfma_f32_16x16x32_bf16 v[104:107], v[164:167], v[196:199], v[104:107]
	v_mfma_f32_16x16x32_bf16 v[92:95], v[156:159], v[204:207], v[92:95]
	v_mfma_f32_16x16x32_bf16 v[88:91], v[164:167], v[204:207], v[88:91]
	v_mfma_f32_16x16x32_bf16 v[76:79], v[156:159], v[212:215], v[76:79]
	v_mfma_f32_16x16x32_bf16 v[72:75], v[164:167], v[212:215], v[72:75]
	s_setprio 0
	s_setprio 1
	v_mfma_f32_16x16x32_bf16 v[116:119], v[168:171], v[184:187], 0
	v_mfma_f32_16x16x32_bf16 v[112:115], v[176:179], v[184:187], 0
	v_mfma_f32_16x16x32_bf16 v[100:103], v[168:171], v[192:195], 0
	v_mfma_f32_16x16x32_bf16 v[96:99], v[176:179], v[192:195], 0
	v_mfma_f32_16x16x32_bf16 v[84:87], v[168:171], v[200:203], 0
	v_mfma_f32_16x16x32_bf16 v[80:83], v[176:179], v[200:203], 0
	v_mfma_f32_16x16x32_bf16 v[68:71], v[168:171], v[208:211], 0
	v_mfma_f32_16x16x32_bf16 v[64:67], v[176:179], v[208:211], 0
	v_mfma_f32_16x16x32_bf16 v[116:119], v[172:175], v[188:191], v[116:119]
	v_mfma_f32_16x16x32_bf16 v[112:115], v[180:183], v[188:191], v[112:115]
	v_mfma_f32_16x16x32_bf16 v[100:103], v[172:175], v[196:199], v[100:103]
	v_mfma_f32_16x16x32_bf16 v[96:99], v[180:183], v[196:199], v[96:99]
	v_mfma_f32_16x16x32_bf16 v[84:87], v[172:175], v[204:207], v[84:87]
	v_mfma_f32_16x16x32_bf16 v[80:83], v[180:183], v[204:207], v[80:83]
	v_mfma_f32_16x16x32_bf16 v[68:71], v[172:175], v[212:215], v[68:71]
	v_mfma_f32_16x16x32_bf16 v[64:67], v[180:183], v[212:215], v[64:67]
	s_setprio 0
	s_barrier
	s_add_i32 s58, s50, s33
	v_lshl_add_u64 v[148:149], s[40:41], 0, v[130:131]
	s_mov_b32 m0, s58
	ds_read_b128 v[184:187], v155 offset:16384
	ds_read_b128 v[188:191], v155 offset:17408
	ds_read_b128 v[192:195], v155 offset:18432
	ds_read_b128 v[196:199], v155 offset:19456
	ds_read_b128 v[200:203], v155 offset:20480
	ds_read_b128 v[204:207], v155 offset:21504
	ds_read_b128 v[208:211], v155 offset:22528
	ds_read_b128 v[212:215], v155 offset:23552
	global_load_lds_dwordx4 v[148:149], off
	s_add_i32 m0, s58, 0x2000
	s_add_u32 s58, s40, 0x40000
	v_lshl_add_u64 v[216:217], s[40:41], 0, v[134:135]
	s_addc_u32 s59, s41, 0
	s_add_i32 s60, s51, s33
	global_load_lds_dwordx4 v[216:217], off
	v_lshl_add_u64 v[218:219], s[58:59], 0, v[130:131]
	s_mov_b32 m0, s60
	v_lshl_add_u64 v[220:221], s[42:43], 0, v[132:133]
	global_load_lds_dwordx4 v[218:219], off
	v_lshl_add_u64 v[218:219], s[58:59], 0, v[134:135]
	s_add_i32 m0, s60, 0x2000
	s_nop 0
	global_load_lds_dwordx4 v[218:219], off
	v_lshl_add_u64 v[218:219], s[42:43], 0, v[128:129]
	s_mov_b32 m0, s27
	s_nop 0
	global_load_lds_dwordx4 v[218:219], off
	s_mov_b32 m0, s44
	s_nop 0
	global_load_lds_dwordx4 v[220:221], off
	s_waitcnt vmcnt(8)
	s_waitcnt lgkmcnt(0)
	s_barrier
	s_setprio 1
	s_waitcnt lgkmcnt(0)
	v_mfma_f32_16x16x32_bf16 v[60:63], v[144:147], v[184:187], 0
	v_mfma_f32_16x16x32_bf16 v[56:59], v[160:163], v[184:187], 0
	v_mfma_f32_16x16x32_bf16 v[44:47], v[144:147], v[192:195], 0
	v_mfma_f32_16x16x32_bf16 v[40:43], v[160:163], v[192:195], 0
	v_mfma_f32_16x16x32_bf16 v[28:31], v[144:147], v[200:203], 0
	v_mfma_f32_16x16x32_bf16 v[24:27], v[160:163], v[200:203], 0
	v_mfma_f32_16x16x32_bf16 v[12:15], v[144:147], v[208:211], 0
	v_mfma_f32_16x16x32_bf16 v[8:11], v[160:163], v[208:211], 0
	v_mfma_f32_16x16x32_bf16 v[60:63], v[156:159], v[188:191], v[60:63]
	v_mfma_f32_16x16x32_bf16 v[56:59], v[164:167], v[188:191], v[56:59]
	v_mfma_f32_16x16x32_bf16 v[44:47], v[156:159], v[196:199], v[44:47]
	v_mfma_f32_16x16x32_bf16 v[40:43], v[164:167], v[196:199], v[40:43]
	v_mfma_f32_16x16x32_bf16 v[28:31], v[156:159], v[204:207], v[28:31]
	v_mfma_f32_16x16x32_bf16 v[24:27], v[164:167], v[204:207], v[24:27]
	v_mfma_f32_16x16x32_bf16 v[12:15], v[156:159], v[212:215], v[12:15]
	v_mfma_f32_16x16x32_bf16 v[8:11], v[164:167], v[212:215], v[8:11]
	s_setprio 0
	s_setprio 1
	v_mfma_f32_16x16x32_bf16 v[52:55], v[168:171], v[184:187], 0
	v_mfma_f32_16x16x32_bf16 v[48:51], v[176:179], v[184:187], 0
	v_mfma_f32_16x16x32_bf16 v[36:39], v[168:171], v[192:195], 0
	v_mfma_f32_16x16x32_bf16 v[32:35], v[176:179], v[192:195], 0
	v_mfma_f32_16x16x32_bf16 v[20:23], v[168:171], v[200:203], 0
	v_mfma_f32_16x16x32_bf16 v[16:19], v[176:179], v[200:203], 0
	v_mfma_f32_16x16x32_bf16 v[4:7], v[168:171], v[208:211], 0
	v_mfma_f32_16x16x32_bf16 v[0:3], v[176:179], v[208:211], 0
	v_mfma_f32_16x16x32_bf16 v[52:55], v[172:175], v[188:191], v[52:55]
	v_mfma_f32_16x16x32_bf16 v[48:51], v[180:183], v[188:191], v[48:51]
	v_mfma_f32_16x16x32_bf16 v[36:39], v[172:175], v[196:199], v[36:39]
	v_mfma_f32_16x16x32_bf16 v[32:35], v[180:183], v[196:199], v[32:35]
	v_mfma_f32_16x16x32_bf16 v[20:23], v[172:175], v[204:207], v[20:23]
	v_mfma_f32_16x16x32_bf16 v[16:19], v[180:183], v[204:207], v[16:19]
	v_mfma_f32_16x16x32_bf16 v[4:7], v[172:175], v[212:215], v[4:7]
	v_mfma_f32_16x16x32_bf16 v[0:3], v[180:183], v[212:215], v[0:3]
	s_setprio 0
	s_barrier
	s_add_i32 s58, 0, 0x18000
	s_add_i32 s59, 0, 0x1c000
	v_add_u32_e32 v164, s58, v151
	v_add_u32_e32 v180, s59, v151
	ds_read_b128 v[144:147], v164
	ds_read_b128 v[156:159], v164 offset:1024
	ds_read_b128 v[160:163], v164 offset:2048
	ds_read_b128 v[164:167], v164 offset:3072
	ds_read_b128 v[168:171], v180
	ds_read_b128 v[172:175], v180 offset:1024
	ds_read_b128 v[176:179], v180 offset:2048
	ds_read_b128 v[180:183], v180 offset:3072
	s_add_u32 s42, s42, 0x40000
	s_addc_u32 s43, s43, 0
	s_mov_b32 m0, s45
	v_lshl_add_u64 v[222:223], s[42:43], 0, v[128:129]
	ds_read_b128 v[184:187], v155 offset:32768
	ds_read_b128 v[188:191], v155 offset:33792
	ds_read_b128 v[192:195], v155 offset:34816
	ds_read_b128 v[196:199], v155 offset:35840
	ds_read_b128 v[200:203], v155 offset:36864
	ds_read_b128 v[204:207], v155 offset:37888
	ds_read_b128 v[208:211], v155 offset:38912
	ds_read_b128 v[212:215], v155 offset:39936
	global_load_lds_dwordx4 v[222:223], off
	v_lshl_add_u64 v[222:223], s[42:43], 0, v[132:133]
	s_mov_b32 m0, s46
	s_nop 0
	global_load_lds_dwordx4 v[222:223], off
	s_waitcnt vmcnt(8)
	s_waitcnt lgkmcnt(0)
	s_barrier
	s_setprio 1
	s_waitcnt lgkmcnt(0)
	v_mfma_f32_16x16x32_bf16 v[124:127], v[144:147], v[184:187], v[124:127]
	v_mfma_f32_16x16x32_bf16 v[120:123], v[160:163], v[184:187], v[120:123]
	v_mfma_f32_16x16x32_bf16 v[108:111], v[144:147], v[192:195], v[108:111]
	v_mfma_f32_16x16x32_bf16 v[104:107], v[160:163], v[192:195], v[104:107]
	v_mfma_f32_16x16x32_bf16 v[92:95], v[144:147], v[200:203], v[92:95]
	v_mfma_f32_16x16x32_bf16 v[88:91], v[160:163], v[200:203], v[88:91]
	v_mfma_f32_16x16x32_bf16 v[76:79], v[144:147], v[208:211], v[76:79]
	v_mfma_f32_16x16x32_bf16 v[72:75], v[160:163], v[208:211], v[72:75]
	v_mfma_f32_16x16x32_bf16 v[124:127], v[156:159], v[188:191], v[124:127]
	v_mfma_f32_16x16x32_bf16 v[120:123], v[164:167], v[188:191], v[120:123]
	v_mfma_f32_16x16x32_bf16 v[108:111], v[156:159], v[196:199], v[108:111]
	v_mfma_f32_16x16x32_bf16 v[104:107], v[164:167], v[196:199], v[104:107]
	v_mfma_f32_16x16x32_bf16 v[92:95], v[156:159], v[204:207], v[92:95]
	v_mfma_f32_16x16x32_bf16 v[88:91], v[164:167], v[204:207], v[88:91]
	v_mfma_f32_16x16x32_bf16 v[76:79], v[156:159], v[212:215], v[76:79]
	v_mfma_f32_16x16x32_bf16 v[72:75], v[164:167], v[212:215], v[72:75]
	s_setprio 0
	s_setprio 1
	v_mfma_f32_16x16x32_bf16 v[116:119], v[168:171], v[184:187], v[116:119]
	v_mfma_f32_16x16x32_bf16 v[112:115], v[176:179], v[184:187], v[112:115]
	v_mfma_f32_16x16x32_bf16 v[100:103], v[168:171], v[192:195], v[100:103]
	v_mfma_f32_16x16x32_bf16 v[96:99], v[176:179], v[192:195], v[96:99]
	v_mfma_f32_16x16x32_bf16 v[84:87], v[168:171], v[200:203], v[84:87]
	v_mfma_f32_16x16x32_bf16 v[80:83], v[176:179], v[200:203], v[80:83]
	v_mfma_f32_16x16x32_bf16 v[68:71], v[168:171], v[208:211], v[68:71]
	v_mfma_f32_16x16x32_bf16 v[64:67], v[176:179], v[208:211], v[64:67]
	v_mfma_f32_16x16x32_bf16 v[116:119], v[172:175], v[188:191], v[116:119]
	v_mfma_f32_16x16x32_bf16 v[112:115], v[180:183], v[188:191], v[112:115]
	v_mfma_f32_16x16x32_bf16 v[100:103], v[172:175], v[196:199], v[100:103]
	v_mfma_f32_16x16x32_bf16 v[96:99], v[180:183], v[196:199], v[96:99]
	v_mfma_f32_16x16x32_bf16 v[84:87], v[172:175], v[204:207], v[84:87]
	v_mfma_f32_16x16x32_bf16 v[80:83], v[180:183], v[204:207], v[80:83]
	v_mfma_f32_16x16x32_bf16 v[68:71], v[172:175], v[212:215], v[68:71]
	v_mfma_f32_16x16x32_bf16 v[64:67], v[180:183], v[212:215], v[64:67]
	s_setprio 0
	s_barrier
	s_add_i32 s42, s58, s33
	v_lshl_add_u64 v[148:149], v[148:149], 0, s[6:7]
	s_mov_b32 m0, s42
	ds_read_b128 v[184:187], v155 offset:49152
	ds_read_b128 v[188:191], v155 offset:50176
	ds_read_b128 v[192:195], v155 offset:51200
	ds_read_b128 v[196:199], v155 offset:52224
	ds_read_b128 v[200:203], v155 offset:53248
	ds_read_b128 v[204:207], v155 offset:54272
	ds_read_b128 v[208:211], v155 offset:55296
	ds_read_b128 v[212:215], v155 offset:56320
	global_load_lds_dwordx4 v[148:149], off
	s_add_i32 m0, s42, 0x2000
	s_add_u32 s40, s40, 0x40080
	v_lshl_add_u64 v[148:149], v[216:217], 0, s[6:7]
	s_addc_u32 s41, s41, 0
	s_add_i32 s42, s59, s33
	global_load_lds_dwordx4 v[148:149], off
	v_lshl_add_u64 v[148:149], s[40:41], 0, v[130:131]
	s_mov_b32 m0, s42
	s_nop 0
	global_load_lds_dwordx4 v[148:149], off
	v_lshl_add_u64 v[148:149], s[40:41], 0, v[134:135]
	s_add_i32 m0, s42, 0x2000
	s_nop 0
	global_load_lds_dwordx4 v[148:149], off
	v_lshl_add_u64 v[148:149], v[218:219], 0, s[6:7]
	s_mov_b32 m0, s48
	s_nop 0
	global_load_lds_dwordx4 v[148:149], off
	v_lshl_add_u64 v[148:149], v[220:221], 0, s[6:7]
	s_mov_b32 m0, s49
	s_nop 0
	global_load_lds_dwordx4 v[148:149], off
	s_waitcnt vmcnt(8)
	s_waitcnt lgkmcnt(0)
	s_barrier
	s_setprio 1
	s_waitcnt lgkmcnt(0)
	v_mfma_f32_16x16x32_bf16 v[60:63], v[144:147], v[184:187], v[60:63]
	v_mfma_f32_16x16x32_bf16 v[56:59], v[160:163], v[184:187], v[56:59]
	v_mfma_f32_16x16x32_bf16 v[44:47], v[144:147], v[192:195], v[44:47]
	v_mfma_f32_16x16x32_bf16 v[40:43], v[160:163], v[192:195], v[40:43]
	v_mfma_f32_16x16x32_bf16 v[28:31], v[144:147], v[200:203], v[28:31]
	v_mfma_f32_16x16x32_bf16 v[24:27], v[160:163], v[200:203], v[24:27]
	v_mfma_f32_16x16x32_bf16 v[12:15], v[144:147], v[208:211], v[12:15]
	v_mfma_f32_16x16x32_bf16 v[8:11], v[160:163], v[208:211], v[8:11]
	v_mfma_f32_16x16x32_bf16 v[60:63], v[156:159], v[188:191], v[60:63]
	v_mfma_f32_16x16x32_bf16 v[56:59], v[164:167], v[188:191], v[56:59]
	v_mfma_f32_16x16x32_bf16 v[44:47], v[156:159], v[196:199], v[44:47]
	v_mfma_f32_16x16x32_bf16 v[40:43], v[164:167], v[196:199], v[40:43]
	v_mfma_f32_16x16x32_bf16 v[28:31], v[156:159], v[204:207], v[28:31]
	v_mfma_f32_16x16x32_bf16 v[24:27], v[164:167], v[204:207], v[24:27]
	v_mfma_f32_16x16x32_bf16 v[12:15], v[156:159], v[212:215], v[12:15]
	v_mfma_f32_16x16x32_bf16 v[8:11], v[164:167], v[212:215], v[8:11]
	s_setprio 0
	s_setprio 1
	v_mfma_f32_16x16x32_bf16 v[52:55], v[168:171], v[184:187], v[52:55]
	v_mfma_f32_16x16x32_bf16 v[48:51], v[176:179], v[184:187], v[48:51]
	v_mfma_f32_16x16x32_bf16 v[36:39], v[168:171], v[192:195], v[36:39]
	v_mfma_f32_16x16x32_bf16 v[32:35], v[176:179], v[192:195], v[32:35]
	v_mfma_f32_16x16x32_bf16 v[20:23], v[168:171], v[200:203], v[20:23]
	v_mfma_f32_16x16x32_bf16 v[16:19], v[176:179], v[200:203], v[16:19]
	v_mfma_f32_16x16x32_bf16 v[4:7], v[168:171], v[208:211], v[4:7]
	v_mfma_f32_16x16x32_bf16 v[0:3], v[176:179], v[208:211], v[0:3]
	v_mfma_f32_16x16x32_bf16 v[52:55], v[172:175], v[188:191], v[52:55]
	v_mfma_f32_16x16x32_bf16 v[48:51], v[180:183], v[188:191], v[48:51]
	v_mfma_f32_16x16x32_bf16 v[36:39], v[172:175], v[196:199], v[36:39]
	v_mfma_f32_16x16x32_bf16 v[32:35], v[180:183], v[196:199], v[32:35]
	v_mfma_f32_16x16x32_bf16 v[20:23], v[172:175], v[204:207], v[20:23]
	v_mfma_f32_16x16x32_bf16 v[16:19], v[180:183], v[204:207], v[16:19]
	v_mfma_f32_16x16x32_bf16 v[4:7], v[172:175], v[212:215], v[4:7]
	v_mfma_f32_16x16x32_bf16 v[0:3], v[180:183], v[212:215], v[0:3]
	s_setprio 0
	s_barrier
	s_add_i32 s57, s57, 2
	s_add_u32 s38, s38, 0x100
	s_addc_u32 s39, s39, 0
	s_add_u32 s55, s55, 0x100
	s_addc_u32 s56, s56, 0
	s_cmp_gt_u32 s57, 13
	s_branch .LBB0_758
